# FFN conv fix-up (down phase): serial 11-iteration per-thread loop replaced by a fully batched version (132 loads in flight, same arithmetic order)
# speedup vs baseline: 1.0121x; 1.0121x over previous
.LBB0_426:
	s_and_b32 s4, s44, 7
	s_cmp_eq_u32 s4, 0
	s_cbranch_scc1 .LBB0_417
	s_and_saveexec_b64 s[24:25], s[40:41]
	s_cbranch_execz .LBB0_416
	s_load_dwordx2 s[4:5], s[0:1], 0x48
	s_mul_i32 s26, s16, 0x10800
	s_mul_i32 s7, s44, 0x16000
	s_mul_hi_i32 s6, s44, 0x16000
	v_lshlrev_b32_e32 v0, 1, v248
	s_waitcnt lgkmcnt(0)
	s_add_u32 s26, s4, s26
	s_mul_hi_i32 s4, s16, 0x10800
	s_addc_u32 s27, s5, s4
	s_add_u32 s28, s39, s7
	s_addc_u32 s29, s43, s6
	s_add_i32 s4, s44, -1
	s_add_i32 s7, s7, 0xfffea000
	s_mul_hi_i32 s4, s4, 0x16000
	s_add_u32 s30, s39, s7
	s_addc_u32 s31, s43, s4
	s_lshl_b32 s46, s44, 8
	s_mov_b64 s[34:35], 0
	s_waitcnt vmcnt(0)
	s_sub_u32 s34, s28, 0xb000
	s_subb_u32 s35, s29, 0
	v_mov_b32_e32 v19, 0xb00
	v_mov_b32_e32 v2, v248
	v_cmp_le_u32_e32 vcc, 0xb00, v2
	s_nop 1
	v_cndmask_b32_e64 v165, 0, 1, vcc
	v_cndmask_b32_e32 v3, 0, v19, vcc
	v_sub_u32_e32 v154, v2, v3
	v_lshlrev_b32_e32 v3, 1, v154
	v_and_b32_e32 v3, 0xff00, v3
	v_and_b32_e32 v4, 0x7f, v154
	v_or_b32_e32 v3, v3, v4
	v_lshlrev_b32_e32 v3, 2, v3
	v_mul_u32_u24_e32 v4, 0x5800, v165
	v_add_u32_e32 v3, v3, v4
	v_add_u32_e32 v4, 0x5800, v3
	v_add_u32_e32 v5, 0xb000, v3
	global_load_dword v22, v5, s[34:35]
	global_load_dword v23, v4, s[34:35]
	global_load_dword v24, v3, s[34:35]
	global_load_dword v25, v5, s[34:35] offset:512
	global_load_dword v26, v4, s[34:35] offset:512
	global_load_dword v27, v3, s[34:35] offset:512
	v_lshlrev_b32_e32 v6, 2, v154
	v_add_u32_e32 v7, 0xb000, v6
	v_add_u32_e32 v8, 0x5800, v6
	global_load_dword v28, v7, s[26:27]
	global_load_dword v29, v8, s[26:27]
	global_load_dword v30, v6, s[26:27]
	v_add_u32_e32 v7, 0x2c00, v7
	v_add_u32_e32 v8, 0x2c00, v8
	v_add_u32_e32 v6, 0x2c00, v6
	global_load_dword v31, v7, s[26:27]
	global_load_dword v32, v8, s[26:27]
	global_load_dword v33, v6, s[26:27]
	v_add_u32_e32 v2, 512, v248
	v_cmp_le_u32_e32 vcc, 0xb00, v2
	s_nop 1
	v_cndmask_b32_e64 v166, 0, 1, vcc
	v_cndmask_b32_e32 v3, 0, v19, vcc
	v_sub_u32_e32 v155, v2, v3
	v_lshlrev_b32_e32 v3, 1, v155
	v_and_b32_e32 v3, 0xff00, v3
	v_and_b32_e32 v4, 0x7f, v155
	v_or_b32_e32 v3, v3, v4
	v_lshlrev_b32_e32 v3, 2, v3
	v_mul_u32_u24_e32 v4, 0x5800, v166
	v_add_u32_e32 v3, v3, v4
	v_add_u32_e32 v4, 0x5800, v3
	v_add_u32_e32 v5, 0xb000, v3
	global_load_dword v34, v5, s[34:35]
	global_load_dword v35, v4, s[34:35]
	global_load_dword v36, v3, s[34:35]
	global_load_dword v37, v5, s[34:35] offset:512
	global_load_dword v38, v4, s[34:35] offset:512
	global_load_dword v39, v3, s[34:35] offset:512
	v_lshlrev_b32_e32 v6, 2, v155
	v_add_u32_e32 v7, 0xb000, v6
	v_add_u32_e32 v8, 0x5800, v6
	global_load_dword v40, v7, s[26:27]
	global_load_dword v41, v8, s[26:27]
	global_load_dword v42, v6, s[26:27]
	v_add_u32_e32 v7, 0x2c00, v7
	v_add_u32_e32 v8, 0x2c00, v8
	v_add_u32_e32 v6, 0x2c00, v6
	global_load_dword v43, v7, s[26:27]
	global_load_dword v44, v8, s[26:27]
	global_load_dword v45, v6, s[26:27]
	v_add_u32_e32 v2, 1024, v248
	v_cmp_le_u32_e32 vcc, 0xb00, v2
	s_nop 1
	v_cndmask_b32_e64 v167, 0, 1, vcc
	v_cndmask_b32_e32 v3, 0, v19, vcc
	v_sub_u32_e32 v156, v2, v3
	v_lshlrev_b32_e32 v3, 1, v156
	v_and_b32_e32 v3, 0xff00, v3
	v_and_b32_e32 v4, 0x7f, v156
	v_or_b32_e32 v3, v3, v4
	v_lshlrev_b32_e32 v3, 2, v3
	v_mul_u32_u24_e32 v4, 0x5800, v167
	v_add_u32_e32 v3, v3, v4
	v_add_u32_e32 v4, 0x5800, v3
	v_add_u32_e32 v5, 0xb000, v3
	global_load_dword v46, v5, s[34:35]
	global_load_dword v47, v4, s[34:35]
	global_load_dword v48, v3, s[34:35]
	global_load_dword v49, v5, s[34:35] offset:512
	global_load_dword v50, v4, s[34:35] offset:512
	global_load_dword v51, v3, s[34:35] offset:512
	v_lshlrev_b32_e32 v6, 2, v156
	v_add_u32_e32 v7, 0xb000, v6
	v_add_u32_e32 v8, 0x5800, v6
	global_load_dword v52, v7, s[26:27]
	global_load_dword v53, v8, s[26:27]
	global_load_dword v54, v6, s[26:27]
	v_add_u32_e32 v7, 0x2c00, v7
	v_add_u32_e32 v8, 0x2c00, v8
	v_add_u32_e32 v6, 0x2c00, v6
	global_load_dword v55, v7, s[26:27]
	global_load_dword v56, v8, s[26:27]
	global_load_dword v57, v6, s[26:27]
	v_add_u32_e32 v2, 1536, v248
	v_cmp_le_u32_e32 vcc, 0xb00, v2
	s_nop 1
	v_cndmask_b32_e64 v168, 0, 1, vcc
	v_cndmask_b32_e32 v3, 0, v19, vcc
	v_sub_u32_e32 v157, v2, v3
	v_lshlrev_b32_e32 v3, 1, v157
	v_and_b32_e32 v3, 0xff00, v3
	v_and_b32_e32 v4, 0x7f, v157
	v_or_b32_e32 v3, v3, v4
	v_lshlrev_b32_e32 v3, 2, v3
	v_mul_u32_u24_e32 v4, 0x5800, v168
	v_add_u32_e32 v3, v3, v4
	v_add_u32_e32 v4, 0x5800, v3
	v_add_u32_e32 v5, 0xb000, v3
	global_load_dword v58, v5, s[34:35]
	global_load_dword v59, v4, s[34:35]
	global_load_dword v60, v3, s[34:35]
	global_load_dword v61, v5, s[34:35] offset:512
	global_load_dword v62, v4, s[34:35] offset:512
	global_load_dword v63, v3, s[34:35] offset:512
	v_lshlrev_b32_e32 v6, 2, v157
	v_add_u32_e32 v7, 0xb000, v6
	v_add_u32_e32 v8, 0x5800, v6
	global_load_dword v64, v7, s[26:27]
	global_load_dword v65, v8, s[26:27]
	global_load_dword v66, v6, s[26:27]
	v_add_u32_e32 v7, 0x2c00, v7
	v_add_u32_e32 v8, 0x2c00, v8
	v_add_u32_e32 v6, 0x2c00, v6
	global_load_dword v67, v7, s[26:27]
	global_load_dword v68, v8, s[26:27]
	global_load_dword v69, v6, s[26:27]
	v_add_u32_e32 v2, 2048, v248
	v_cmp_le_u32_e32 vcc, 0xb00, v2
	s_nop 1
	v_cndmask_b32_e64 v169, 0, 1, vcc
	v_cndmask_b32_e32 v3, 0, v19, vcc
	v_sub_u32_e32 v158, v2, v3
	v_lshlrev_b32_e32 v3, 1, v158
	v_and_b32_e32 v3, 0xff00, v3
	v_and_b32_e32 v4, 0x7f, v158
	v_or_b32_e32 v3, v3, v4
	v_lshlrev_b32_e32 v3, 2, v3
	v_mul_u32_u24_e32 v4, 0x5800, v169
	v_add_u32_e32 v3, v3, v4
	v_add_u32_e32 v4, 0x5800, v3
	v_add_u32_e32 v5, 0xb000, v3
	global_load_dword v70, v5, s[34:35]
	global_load_dword v71, v4, s[34:35]
	global_load_dword v72, v3, s[34:35]
	global_load_dword v73, v5, s[34:35] offset:512
	global_load_dword v74, v4, s[34:35] offset:512
	global_load_dword v75, v3, s[34:35] offset:512
	v_lshlrev_b32_e32 v6, 2, v158
	v_add_u32_e32 v7, 0xb000, v6
	v_add_u32_e32 v8, 0x5800, v6
	global_load_dword v76, v7, s[26:27]
	global_load_dword v77, v8, s[26:27]
	global_load_dword v78, v6, s[26:27]
	v_add_u32_e32 v7, 0x2c00, v7
	v_add_u32_e32 v8, 0x2c00, v8
	v_add_u32_e32 v6, 0x2c00, v6
	global_load_dword v79, v7, s[26:27]
	global_load_dword v80, v8, s[26:27]
	global_load_dword v81, v6, s[26:27]
	v_add_u32_e32 v2, 2560, v248
	v_cmp_le_u32_e32 vcc, 0xb00, v2
	s_nop 1
	v_cndmask_b32_e64 v170, 0, 1, vcc
	v_cndmask_b32_e32 v3, 0, v19, vcc
	v_sub_u32_e32 v159, v2, v3
	v_lshlrev_b32_e32 v3, 1, v159
	v_and_b32_e32 v3, 0xff00, v3
	v_and_b32_e32 v4, 0x7f, v159
	v_or_b32_e32 v3, v3, v4
	v_lshlrev_b32_e32 v3, 2, v3
	v_mul_u32_u24_e32 v4, 0x5800, v170
	v_add_u32_e32 v3, v3, v4
	v_add_u32_e32 v4, 0x5800, v3
	v_add_u32_e32 v5, 0xb000, v3
	global_load_dword v82, v5, s[34:35]
	global_load_dword v83, v4, s[34:35]
	global_load_dword v84, v3, s[34:35]
	global_load_dword v85, v5, s[34:35] offset:512
	global_load_dword v86, v4, s[34:35] offset:512
	global_load_dword v87, v3, s[34:35] offset:512
	v_lshlrev_b32_e32 v6, 2, v159
	v_add_u32_e32 v7, 0xb000, v6
	v_add_u32_e32 v8, 0x5800, v6
	global_load_dword v88, v7, s[26:27]
	global_load_dword v89, v8, s[26:27]
	global_load_dword v90, v6, s[26:27]
	v_add_u32_e32 v7, 0x2c00, v7
	v_add_u32_e32 v8, 0x2c00, v8
	v_add_u32_e32 v6, 0x2c00, v6
	global_load_dword v91, v7, s[26:27]
	global_load_dword v92, v8, s[26:27]
	global_load_dword v93, v6, s[26:27]
	v_add_u32_e32 v2, 3072, v248
	v_cmp_le_u32_e32 vcc, 0xb00, v2
	s_nop 1
	v_cndmask_b32_e64 v171, 0, 1, vcc
	v_cndmask_b32_e32 v3, 0, v19, vcc
	v_sub_u32_e32 v160, v2, v3
	v_lshlrev_b32_e32 v3, 1, v160
	v_and_b32_e32 v3, 0xff00, v3
	v_and_b32_e32 v4, 0x7f, v160
	v_or_b32_e32 v3, v3, v4
	v_lshlrev_b32_e32 v3, 2, v3
	v_mul_u32_u24_e32 v4, 0x5800, v171
	v_add_u32_e32 v3, v3, v4
	v_add_u32_e32 v4, 0x5800, v3
	v_add_u32_e32 v5, 0xb000, v3
	global_load_dword v94, v5, s[34:35]
	global_load_dword v95, v4, s[34:35]
	global_load_dword v96, v3, s[34:35]
	global_load_dword v97, v5, s[34:35] offset:512
	global_load_dword v98, v4, s[34:35] offset:512
	global_load_dword v99, v3, s[34:35] offset:512
	v_lshlrev_b32_e32 v6, 2, v160
	v_add_u32_e32 v7, 0xb000, v6
	v_add_u32_e32 v8, 0x5800, v6
	global_load_dword v100, v7, s[26:27]
	global_load_dword v101, v8, s[26:27]
	global_load_dword v102, v6, s[26:27]
	v_add_u32_e32 v7, 0x2c00, v7
	v_add_u32_e32 v8, 0x2c00, v8
	v_add_u32_e32 v6, 0x2c00, v6
	global_load_dword v103, v7, s[26:27]
	global_load_dword v104, v8, s[26:27]
	global_load_dword v105, v6, s[26:27]
	v_add_u32_e32 v2, 3584, v248
	v_cmp_le_u32_e32 vcc, 0xb00, v2
	s_nop 1
	v_cndmask_b32_e64 v172, 0, 1, vcc
	v_cndmask_b32_e32 v3, 0, v19, vcc
	v_sub_u32_e32 v161, v2, v3
	v_lshlrev_b32_e32 v3, 1, v161
	v_and_b32_e32 v3, 0xff00, v3
	v_and_b32_e32 v4, 0x7f, v161
	v_or_b32_e32 v3, v3, v4
	v_lshlrev_b32_e32 v3, 2, v3
	v_mul_u32_u24_e32 v4, 0x5800, v172
	v_add_u32_e32 v3, v3, v4
	v_add_u32_e32 v4, 0x5800, v3
	v_add_u32_e32 v5, 0xb000, v3
	global_load_dword v106, v5, s[34:35]
	global_load_dword v107, v4, s[34:35]
	global_load_dword v108, v3, s[34:35]
	global_load_dword v109, v5, s[34:35] offset:512
	global_load_dword v110, v4, s[34:35] offset:512
	global_load_dword v111, v3, s[34:35] offset:512
	v_lshlrev_b32_e32 v6, 2, v161
	v_add_u32_e32 v7, 0xb000, v6
	v_add_u32_e32 v8, 0x5800, v6
	global_load_dword v112, v7, s[26:27]
	global_load_dword v113, v8, s[26:27]
	global_load_dword v114, v6, s[26:27]
	v_add_u32_e32 v7, 0x2c00, v7
	v_add_u32_e32 v8, 0x2c00, v8
	v_add_u32_e32 v6, 0x2c00, v6
	global_load_dword v115, v7, s[26:27]
	global_load_dword v116, v8, s[26:27]
	global_load_dword v117, v6, s[26:27]
	v_add_u32_e32 v2, 4096, v248
	v_cmp_le_u32_e32 vcc, 0xb00, v2
	s_nop 1
	v_cndmask_b32_e64 v173, 0, 1, vcc
	v_cndmask_b32_e32 v3, 0, v19, vcc
	v_sub_u32_e32 v162, v2, v3
	v_lshlrev_b32_e32 v3, 1, v162
	v_and_b32_e32 v3, 0xff00, v3
	v_and_b32_e32 v4, 0x7f, v162
	v_or_b32_e32 v3, v3, v4
	v_lshlrev_b32_e32 v3, 2, v3
	v_mul_u32_u24_e32 v4, 0x5800, v173
	v_add_u32_e32 v3, v3, v4
	v_add_u32_e32 v4, 0x5800, v3
	v_add_u32_e32 v5, 0xb000, v3
	global_load_dword v118, v5, s[34:35]
	global_load_dword v119, v4, s[34:35]
	global_load_dword v120, v3, s[34:35]
	global_load_dword v121, v5, s[34:35] offset:512
	global_load_dword v122, v4, s[34:35] offset:512
	global_load_dword v123, v3, s[34:35] offset:512
	v_lshlrev_b32_e32 v6, 2, v162
	v_add_u32_e32 v7, 0xb000, v6
	v_add_u32_e32 v8, 0x5800, v6
	global_load_dword v124, v7, s[26:27]
	global_load_dword v125, v8, s[26:27]
	global_load_dword v126, v6, s[26:27]
	v_add_u32_e32 v7, 0x2c00, v7
	v_add_u32_e32 v8, 0x2c00, v8
	v_add_u32_e32 v6, 0x2c00, v6
	global_load_dword v127, v7, s[26:27]
	global_load_dword v128, v8, s[26:27]
	global_load_dword v129, v6, s[26:27]
	v_add_u32_e32 v2, 4608, v248
	v_cmp_le_u32_e32 vcc, 0xb00, v2
	s_nop 1
	v_cndmask_b32_e64 v174, 0, 1, vcc
	v_cndmask_b32_e32 v3, 0, v19, vcc
	v_sub_u32_e32 v163, v2, v3
	v_lshlrev_b32_e32 v3, 1, v163
	v_and_b32_e32 v3, 0xff00, v3
	v_and_b32_e32 v4, 0x7f, v163
	v_or_b32_e32 v3, v3, v4
	v_lshlrev_b32_e32 v3, 2, v3
	v_mul_u32_u24_e32 v4, 0x5800, v174
	v_add_u32_e32 v3, v3, v4
	v_add_u32_e32 v4, 0x5800, v3
	v_add_u32_e32 v5, 0xb000, v3
	global_load_dword v130, v5, s[34:35]
	global_load_dword v131, v4, s[34:35]
	global_load_dword v132, v3, s[34:35]
	global_load_dword v133, v5, s[34:35] offset:512
	global_load_dword v134, v4, s[34:35] offset:512
	global_load_dword v135, v3, s[34:35] offset:512
	v_lshlrev_b32_e32 v6, 2, v163
	v_add_u32_e32 v7, 0xb000, v6
	v_add_u32_e32 v8, 0x5800, v6
	global_load_dword v136, v7, s[26:27]
	global_load_dword v137, v8, s[26:27]
	global_load_dword v138, v6, s[26:27]
	v_add_u32_e32 v7, 0x2c00, v7
	v_add_u32_e32 v8, 0x2c00, v8
	v_add_u32_e32 v6, 0x2c00, v6
	global_load_dword v139, v7, s[26:27]
	global_load_dword v140, v8, s[26:27]
	global_load_dword v141, v6, s[26:27]
	v_add_u32_e32 v2, 5120, v248
	v_cmp_le_u32_e32 vcc, 0xb00, v2
	s_nop 1
	v_cndmask_b32_e64 v175, 0, 1, vcc
	v_cndmask_b32_e32 v3, 0, v19, vcc
	v_sub_u32_e32 v164, v2, v3
	v_lshlrev_b32_e32 v3, 1, v164
	v_and_b32_e32 v3, 0xff00, v3
	v_and_b32_e32 v4, 0x7f, v164
	v_or_b32_e32 v3, v3, v4
	v_lshlrev_b32_e32 v3, 2, v3
	v_mul_u32_u24_e32 v4, 0x5800, v175
	v_add_u32_e32 v3, v3, v4
	v_add_u32_e32 v4, 0x5800, v3
	v_add_u32_e32 v5, 0xb000, v3
	global_load_dword v142, v5, s[34:35]
	global_load_dword v143, v4, s[34:35]
	global_load_dword v144, v3, s[34:35]
	global_load_dword v145, v5, s[34:35] offset:512
	global_load_dword v146, v4, s[34:35] offset:512
	global_load_dword v147, v3, s[34:35] offset:512
	v_lshlrev_b32_e32 v6, 2, v164
	v_add_u32_e32 v7, 0xb000, v6
	v_add_u32_e32 v8, 0x5800, v6
	global_load_dword v148, v7, s[26:27]
	global_load_dword v149, v8, s[26:27]
	global_load_dword v150, v6, s[26:27]
	v_add_u32_e32 v7, 0x2c00, v7
	v_add_u32_e32 v8, 0x2c00, v8
	v_add_u32_e32 v6, 0x2c00, v6
	global_load_dword v151, v7, s[26:27]
	global_load_dword v152, v8, s[26:27]
	global_load_dword v153, v6, s[26:27]
	s_waitcnt vmcnt(0)
	v_mul_f32_e32 v23, v23, v29
	v_mul_f32_e32 v26, v26, v32
	v_fmac_f32_e32 v23, v22, v28
	v_fmac_f32_e32 v26, v25, v31
	v_fmac_f32_e32 v23, v24, v30
	v_fmac_f32_e32 v26, v27, v33
	v_mul_f32_e32 v26, v23, v26
	v_mul_f32_e32 v23, 0xbfb8aa3b, v23
	v_mul_f32_e32 v35, v35, v41
	v_mul_f32_e32 v38, v38, v44
	v_fmac_f32_e32 v35, v34, v40
	v_fmac_f32_e32 v38, v37, v43
	v_fmac_f32_e32 v35, v36, v42
	v_fmac_f32_e32 v38, v39, v45
	v_mul_f32_e32 v38, v35, v38
	v_mul_f32_e32 v35, 0xbfb8aa3b, v35
	v_mul_f32_e32 v47, v47, v53
	v_mul_f32_e32 v50, v50, v56
	v_fmac_f32_e32 v47, v46, v52
	v_fmac_f32_e32 v50, v49, v55
	v_fmac_f32_e32 v47, v48, v54
	v_fmac_f32_e32 v50, v51, v57
	v_mul_f32_e32 v50, v47, v50
	v_mul_f32_e32 v47, 0xbfb8aa3b, v47
	v_mul_f32_e32 v59, v59, v65
	v_mul_f32_e32 v62, v62, v68
	v_fmac_f32_e32 v59, v58, v64
	v_fmac_f32_e32 v62, v61, v67
	v_fmac_f32_e32 v59, v60, v66
	v_fmac_f32_e32 v62, v63, v69
	v_mul_f32_e32 v62, v59, v62
	v_mul_f32_e32 v59, 0xbfb8aa3b, v59
	v_mul_f32_e32 v71, v71, v77
	v_mul_f32_e32 v74, v74, v80
	v_fmac_f32_e32 v71, v70, v76
	v_fmac_f32_e32 v74, v73, v79
	v_fmac_f32_e32 v71, v72, v78
	v_fmac_f32_e32 v74, v75, v81
	v_mul_f32_e32 v74, v71, v74
	v_mul_f32_e32 v71, 0xbfb8aa3b, v71
	v_mul_f32_e32 v83, v83, v89
	v_mul_f32_e32 v86, v86, v92
	v_fmac_f32_e32 v83, v82, v88
	v_fmac_f32_e32 v86, v85, v91
	v_fmac_f32_e32 v83, v84, v90
	v_fmac_f32_e32 v86, v87, v93
	v_mul_f32_e32 v86, v83, v86
	v_mul_f32_e32 v83, 0xbfb8aa3b, v83
	v_mul_f32_e32 v95, v95, v101
	v_mul_f32_e32 v98, v98, v104
	v_fmac_f32_e32 v95, v94, v100
	v_fmac_f32_e32 v98, v97, v103
	v_fmac_f32_e32 v95, v96, v102
	v_fmac_f32_e32 v98, v99, v105
	v_mul_f32_e32 v98, v95, v98
	v_mul_f32_e32 v95, 0xbfb8aa3b, v95
	v_mul_f32_e32 v107, v107, v113
	v_mul_f32_e32 v110, v110, v116
	v_fmac_f32_e32 v107, v106, v112
	v_fmac_f32_e32 v110, v109, v115
	v_fmac_f32_e32 v107, v108, v114
	v_fmac_f32_e32 v110, v111, v117
	v_mul_f32_e32 v110, v107, v110
	v_mul_f32_e32 v107, 0xbfb8aa3b, v107
	v_mul_f32_e32 v119, v119, v125
	v_mul_f32_e32 v122, v122, v128
	v_fmac_f32_e32 v119, v118, v124
	v_fmac_f32_e32 v122, v121, v127
	v_fmac_f32_e32 v119, v120, v126
	v_fmac_f32_e32 v122, v123, v129
	v_mul_f32_e32 v122, v119, v122
	v_mul_f32_e32 v119, 0xbfb8aa3b, v119
	v_mul_f32_e32 v131, v131, v137
	v_mul_f32_e32 v134, v134, v140
	v_fmac_f32_e32 v131, v130, v136
	v_fmac_f32_e32 v134, v133, v139
	v_fmac_f32_e32 v131, v132, v138
	v_fmac_f32_e32 v134, v135, v141
	v_mul_f32_e32 v134, v131, v134
	v_mul_f32_e32 v131, 0xbfb8aa3b, v131
	v_mul_f32_e32 v143, v143, v149
	v_mul_f32_e32 v146, v146, v152
	v_fmac_f32_e32 v143, v142, v148
	v_fmac_f32_e32 v146, v145, v151
	v_fmac_f32_e32 v143, v144, v150
	v_fmac_f32_e32 v146, v147, v153
	v_mul_f32_e32 v146, v143, v146
	v_mul_f32_e32 v143, 0xbfb8aa3b, v143
	v_exp_f32_e32 v23, v23
	v_exp_f32_e32 v35, v35
	v_exp_f32_e32 v47, v47
	v_exp_f32_e32 v59, v59
	v_exp_f32_e32 v71, v71
	v_exp_f32_e32 v83, v83
	v_exp_f32_e32 v95, v95
	v_exp_f32_e32 v107, v107
	v_exp_f32_e32 v119, v119
	v_exp_f32_e32 v131, v131
	v_exp_f32_e32 v143, v143
	s_nop 0
	v_add_f32_e32 v23, 1.0, v23
	v_add_f32_e32 v35, 1.0, v35
	v_add_f32_e32 v47, 1.0, v47
	v_add_f32_e32 v59, 1.0, v59
	v_add_f32_e32 v71, 1.0, v71
	v_add_f32_e32 v83, 1.0, v83
	v_add_f32_e32 v95, 1.0, v95
	v_add_f32_e32 v107, 1.0, v107
	v_add_f32_e32 v119, 1.0, v119
	v_add_f32_e32 v131, 1.0, v131
	v_add_f32_e32 v143, 1.0, v143
	v_rcp_f32_e32 v23, v23
	v_rcp_f32_e32 v35, v35
	v_rcp_f32_e32 v47, v47
	v_rcp_f32_e32 v59, v59
	v_rcp_f32_e32 v71, v71
	v_rcp_f32_e32 v83, v83
	v_rcp_f32_e32 v95, v95
	v_rcp_f32_e32 v107, v107
	v_rcp_f32_e32 v119, v119
	v_rcp_f32_e32 v131, v131
	v_rcp_f32_e32 v143, v143
	s_nop 0
	v_mul_f32_e32 v23, v26, v23
	v_cvt_pk_bf16_f32 v23, v23, v23
	v_add_u32_e32 v2, s46, v165
	v_mov_b64_e32 v[4:5], s[22:23]
	v_mad_i64_i32 v[4:5], s[4:5], v2, s92, v[4:5]
	v_lshlrev_b32_e32 v2, 1, v154
	v_mov_b32_e32 v3, 0
	v_lshl_add_u64 v[4:5], v[4:5], 0, v[2:3]
	global_store_short v[4:5], v23, off
	v_mul_f32_e32 v35, v38, v35
	v_cvt_pk_bf16_f32 v35, v35, v35
	v_add_u32_e32 v2, s46, v166
	v_mov_b64_e32 v[4:5], s[22:23]
	v_mad_i64_i32 v[4:5], s[4:5], v2, s92, v[4:5]
	v_lshlrev_b32_e32 v2, 1, v155
	v_mov_b32_e32 v3, 0
	v_lshl_add_u64 v[4:5], v[4:5], 0, v[2:3]
	global_store_short v[4:5], v35, off
	v_mul_f32_e32 v47, v50, v47
	v_cvt_pk_bf16_f32 v47, v47, v47
	v_add_u32_e32 v2, s46, v167
	v_mov_b64_e32 v[4:5], s[22:23]
	v_mad_i64_i32 v[4:5], s[4:5], v2, s92, v[4:5]
	v_lshlrev_b32_e32 v2, 1, v156
	v_mov_b32_e32 v3, 0
	v_lshl_add_u64 v[4:5], v[4:5], 0, v[2:3]
	global_store_short v[4:5], v47, off
	v_mul_f32_e32 v59, v62, v59
	v_cvt_pk_bf16_f32 v59, v59, v59
	v_add_u32_e32 v2, s46, v168
	v_mov_b64_e32 v[4:5], s[22:23]
	v_mad_i64_i32 v[4:5], s[4:5], v2, s92, v[4:5]
	v_lshlrev_b32_e32 v2, 1, v157
	v_mov_b32_e32 v3, 0
	v_lshl_add_u64 v[4:5], v[4:5], 0, v[2:3]
	global_store_short v[4:5], v59, off
	v_mul_f32_e32 v71, v74, v71
	v_cvt_pk_bf16_f32 v71, v71, v71
	v_add_u32_e32 v2, s46, v169
	v_mov_b64_e32 v[4:5], s[22:23]
	v_mad_i64_i32 v[4:5], s[4:5], v2, s92, v[4:5]
	v_lshlrev_b32_e32 v2, 1, v158
	v_mov_b32_e32 v3, 0
	v_lshl_add_u64 v[4:5], v[4:5], 0, v[2:3]
	global_store_short v[4:5], v71, off
	v_mul_f32_e32 v83, v86, v83
	v_cvt_pk_bf16_f32 v83, v83, v83
	v_add_u32_e32 v2, s46, v170
	v_mov_b64_e32 v[4:5], s[22:23]
	v_mad_i64_i32 v[4:5], s[4:5], v2, s92, v[4:5]
	v_lshlrev_b32_e32 v2, 1, v159
	v_mov_b32_e32 v3, 0
	v_lshl_add_u64 v[4:5], v[4:5], 0, v[2:3]
	global_store_short v[4:5], v83, off
	v_mul_f32_e32 v95, v98, v95
	v_cvt_pk_bf16_f32 v95, v95, v95
	v_add_u32_e32 v2, s46, v171
	v_mov_b64_e32 v[4:5], s[22:23]
	v_mad_i64_i32 v[4:5], s[4:5], v2, s92, v[4:5]
	v_lshlrev_b32_e32 v2, 1, v160
	v_mov_b32_e32 v3, 0
	v_lshl_add_u64 v[4:5], v[4:5], 0, v[2:3]
	global_store_short v[4:5], v95, off
	v_mul_f32_e32 v107, v110, v107
	v_cvt_pk_bf16_f32 v107, v107, v107
	v_add_u32_e32 v2, s46, v172
	v_mov_b64_e32 v[4:5], s[22:23]
	v_mad_i64_i32 v[4:5], s[4:5], v2, s92, v[4:5]
	v_lshlrev_b32_e32 v2, 1, v161
	v_mov_b32_e32 v3, 0
	v_lshl_add_u64 v[4:5], v[4:5], 0, v[2:3]
	global_store_short v[4:5], v107, off
	v_mul_f32_e32 v119, v122, v119
	v_cvt_pk_bf16_f32 v119, v119, v119
	v_add_u32_e32 v2, s46, v173
	v_mov_b64_e32 v[4:5], s[22:23]
	v_mad_i64_i32 v[4:5], s[4:5], v2, s92, v[4:5]
	v_lshlrev_b32_e32 v2, 1, v162
	v_mov_b32_e32 v3, 0
	v_lshl_add_u64 v[4:5], v[4:5], 0, v[2:3]
	global_store_short v[4:5], v119, off
	v_mul_f32_e32 v131, v134, v131
	v_cvt_pk_bf16_f32 v131, v131, v131
	v_add_u32_e32 v2, s46, v174
	v_mov_b64_e32 v[4:5], s[22:23]
	v_mad_i64_i32 v[4:5], s[4:5], v2, s92, v[4:5]
	v_lshlrev_b32_e32 v2, 1, v163
	v_mov_b32_e32 v3, 0
	v_lshl_add_u64 v[4:5], v[4:5], 0, v[2:3]
	global_store_short v[4:5], v131, off
	v_mul_f32_e32 v143, v146, v143
	v_cvt_pk_bf16_f32 v143, v143, v143
	v_add_u32_e32 v2, s46, v175
	v_mov_b64_e32 v[4:5], s[22:23]
	v_mad_i64_i32 v[4:5], s[4:5], v2, s92, v[4:5]
	v_lshlrev_b32_e32 v2, 1, v164
	v_mov_b32_e32 v3, 0
	v_lshl_add_u64 v[4:5], v[4:5], 0, v[2:3]
	global_store_short v[4:5], v143, off
	s_branch .LBB0_416
